# P9 up-proj: units of the last M tile (4 valid rows) skip the MFMA groups of rows 64..255 (accumulators stay zero, rows masked in the conv epilogue)
# baseline (speedup 1.0000x reference)
.LBB0_1029:
	s_add_i32 s57, s5, s0
	s_mul_hi_i32 s0, s57, 0x2e8ba2e9
	s_lshr_b32 s1, s0, 31
	s_ashr_i32 s58, s0, 5
	s_add_i32 s58, s58, s1
	s_lshl_b32 s1, s58, 3
	s_sub_i32 s0, 0x82, s1
	s_min_i32 s4, s0, 8
	s_abs_i32 s0, s4
	v_cvt_f32_u32_e32 v0, s0
	s_sub_i32 s28, 0, s0
	s_mul_i32 s5, s58, 0xb0
	s_sub_i32 s5, s57, s5
	v_rcp_iflag_f32_e32 v0, v0
	s_abs_i32 s10, s5
	s_xor_b32 s11, s5, s4
	s_ashr_i32 s11, s11, 31
	v_mul_f32_e32 v0, 0x4f7ffffe, v0
	v_cvt_u32_f32_e32 v0, v0
	s_mov_b32 s62, 16
	v_readfirstlane_b32 s29, v0
	v_mov_b32_e32 v0, v191
	s_mul_i32 s28, s28, s29
	v_bfe_i32 v2, v0, 27, 1
	v_lshlrev_b32_e32 v4, 4, v0
	v_lshrrev_b32_e32 v2, 22, v2
	v_add_u32_e32 v2, v4, v2
	v_and_b32_e32 v2, 0xfffffc00, v2
	v_sub_u32_e32 v2, v4, v2
	v_lshrrev_b32_e32 v3, 4, v2
	v_bitop3_b32 v3, v3, v2, 32 bitop3:0x6c
	v_ashrrev_i32_e32 v2, 31, v2
	v_lshrrev_b32_e32 v2, 26, v2
	v_ashrrev_i32_e32 v1, 31, v0
	v_add_u32_e32 v2, v3, v2
	v_lshrrev_b32_e32 v1, 26, v1
	v_ashrrev_i32_e32 v2, 6, v2
	s_mul_hi_u32 s28, s29, s28
	v_add_u32_e32 v1, v0, v1
	v_mul_i32_i24_e32 v7, 64, v2
	s_add_i32 s29, s29, s28
	v_ashrrev_i32_e32 v1, 6, v1
	v_sub_u32_e32 v3, v3, v7
	s_mul_hi_u32 s28, s10, s29
	v_lshlrev_b32_e32 v5, 3, v1
	v_lshlrev_b32_e32 v6, 5, v1
	v_ashrrev_i16_sdwa v3, v145, sext(v3) dst_sel:DWORD dst_unused:UNUSED_PAD src0_sel:DWORD src1_sel:BYTE_0
	s_mul_i32 s29, s28, s0
	v_and_b32_e32 v5, -16, v5
	v_and_b32_e32 v6, 32, v6
	v_bfe_i32 v3, v3, 0, 16
	s_sub_i32 s10, s10, s29
	v_add_u32_e32 v5, v2, v5
	v_and_b32_e32 v9, 3, v2
	v_add_lshl_u32 v6, v6, v3, 1
	s_add_i32 s36, s28, 1
	s_sub_i32 s29, s10, s0
	v_lshlrev_b32_e32 v7, 1, v5
	v_lshrrev_b32_e32 v8, 2, v5
	v_and_or_b32 v9, v5, s52, v9
	v_lshl_add_u32 v132, v5, 11, v6
	v_add_u32_e32 v5, 0x2000, v4
	s_cmp_ge_u32 s10, s0
	v_ashrrev_i32_e32 v4, 31, v5
	s_cselect_b32 s28, s36, s28
	v_lshrrev_b32_e32 v4, 22, v4
	s_cselect_b32 s10, s29, s10
	s_add_i32 s29, s28, 1
	v_and_b32_e32 v7, 24, v7
	v_and_b32_e32 v8, 4, v8
	v_add_u32_e32 v4, v5, v4
	s_cmp_ge_u32 s10, s0
	v_or3_b32 v7, v9, v8, v7
	v_ashrrev_i32_e32 v4, 10, v4
	s_cselect_b32 s0, s29, s28
	v_lshl_add_u32 v130, v7, 11, v6
	v_mul_i32_i24_e32 v6, 0x400, v4
	s_xor_b32 s0, s0, s11
	v_sub_u32_e32 v5, v5, v6
	s_sub_i32 s0, s0, s11
	v_lshrrev_b32_e32 v6, 4, v5
	s_mul_i32 s59, s0, s4
	v_bitop3_b32 v6, v6, v5, 32 bitop3:0x6c
	v_lshlrev_b32_e32 v5, 3, v4
	s_sub_i32 s4, s5, s59
	v_and_b32_e32 v7, -16, v5
	v_ashrrev_i32_e32 v5, 31, v6
	s_add_i32 s1, s1, s4
	v_readfirstlane_b32 s60, v0
	v_lshrrev_b32_e32 v5, 26, v5
	s_ashr_i32 s28, s60, 6
	v_add_u32_e32 v8, v6, v5
	s_mul_hi_i32 s29, s1, 0x7f000
	s_cmp_eq_u32 s1, 0x81
	s_cselect_b32 s92, 1, 0
	s_lshr_b32 s93, s28, 2
	s_and_b32 s93, s93, s92
	s_mul_i32 s36, s1, 0x7f000
	s_ashr_i32 s1, s0, 31
	v_ashrrev_i32_e32 v5, 6, v8
	v_and_b32_e32 v8, 0xc0, v8
	s_ashr_i32 s37, s60, 8
	s_lshl_b32 s63, s28, 10
	s_lshl_b64 s[4:5], s[0:1], 19
	v_add_u32_e32 v7, v5, v7
	v_sub_u32_e32 v6, v6, v8
	s_add_u32 s4, s3, s4
	v_lshlrev_b32_e32 v9, 5, v4
	v_ashrrev_i16_sdwa v6, v145, sext(v6) dst_sel:DWORD dst_unused:UNUSED_PAD src0_sel:DWORD src1_sel:BYTE_0
	v_lshlrev_b32_e32 v8, 1, v7
	v_lshrrev_b32_e32 v10, 2, v7
	v_and_b32_e32 v11, 3, v5
	s_addc_u32 s5, s44, s5
	s_add_i32 s64, s63, 0
	v_and_b32_e32 v9, 32, v9
	v_bfe_i32 v6, v6, 0, 16
	v_and_b32_e32 v8, 24, v8
	v_and_b32_e32 v10, 4, v10
	v_and_or_b32 v11, v7, s52, v11
	s_add_i32 m0, s64, 0x10000
	v_or3_b32 v8, v11, v10, v8
	v_add_lshl_u32 v9, v9, v6, 1
	global_load_lds_dwordx4 v130, s[4:5]
	s_add_i32 m0, s64, 0x12000
	v_lshl_add_u32 v136, v8, 11, v9
	s_add_u32 s10, s4, 0x40000
	global_load_lds_dwordx4 v136, s[4:5]
	s_addc_u32 s11, s5, 0
	s_add_i32 m0, s64, 0x14000
	v_lshl_add_u32 v134, v7, 11, v9
	global_load_lds_dwordx4 v130, s[10:11]
	s_add_i32 m0, s64, 0x16000
	s_nop 0
	global_load_lds_dwordx4 v136, s[10:11]
	s_add_u32 s10, s48, s36
	s_addc_u32 s11, s49, s29
	s_add_i32 s65, s64, 0x2000
	s_mov_b32 m0, s64
	s_add_u32 s42, s10, 0x40000
	global_load_lds_dwordx4 v132, s[10:11]
	s_mov_b32 m0, s65
	s_addc_u32 s43, s11, 0
	s_add_i32 s66, s64, 0x4000
	global_load_lds_dwordx4 v134, s[10:11]
	s_mov_b32 m0, s66
	s_add_i32 s67, s64, 0x6000
	global_load_lds_dwordx4 v132, s[42:43]
	s_mov_b32 m0, s67
	s_cmp_lg_u32 s37, 1
	global_load_lds_dwordx4 v134, s[42:43]
	s_cbranch_scc1 .LBB0_1031
	s_barrier

.LBB0_1033:
	s_cmp_lg_u32 s92, 0
	s_cselect_b64 vcc, -1, 0
	s_add_i32 s71, s36, 2
	s_add_u32 s37, s28, 0xe5fbf080
	s_addc_u32 s42, s29, -1
	s_cmp_lg_u32 s70, s36
	s_cselect_b32 s36, s37, 0
	s_cselect_b32 s72, s42, 0
	s_add_u32 s42, s10, s36
	s_addc_u32 s43, s11, s72
	s_add_i32 s73, 0, 0x10000
	s_add_u32 s36, s4, s36
	s_addc_u32 s37, s5, s72
	s_add_i32 s74, 0, 0x14000
	v_add_u32_e32 v160, s73, v146
	v_add_u32_e32 v176, s74, v146
	ds_read_b128 v[148:151], v160
	ds_read_b128 v[152:155], v160 offset:1024
	ds_read_b128 v[156:159], v160 offset:2048
	ds_read_b128 v[160:163], v160 offset:3072
	ds_read_b128 v[164:167], v176
	ds_read_b128 v[168:171], v176 offset:1024
	ds_read_b128 v[172:175], v176 offset:2048
	ds_read_b128 v[176:179], v176 offset:3072
	v_lshl_add_u64 v[188:189], v[138:139], 0, s[28:29]
	s_add_i32 m0, s64, 0xc000
	ds_read_b128 v[180:183], v147
	ds_read_b128 v[184:187], v147 offset:1024
	ds_read_b128 v[192:195], v147 offset:2048
	ds_read_b128 v[196:199], v147 offset:3072
	ds_read_b128 v[200:203], v147 offset:4096
	ds_read_b128 v[204:207], v147 offset:5120
	ds_read_b128 v[208:211], v147 offset:6144
	ds_read_b128 v[212:215], v147 offset:7168
	global_load_lds_dwordx4 v[188:189], off
	v_lshl_add_u64 v[188:189], v[140:141], 0, s[28:29]
	s_add_i32 m0, s64, 0xe000
	s_nop 0
	global_load_lds_dwordx4 v[188:189], off
	s_waitcnt vmcnt(8)
	s_waitcnt lgkmcnt(0)
	s_barrier
	s_setprio 1
	s_waitcnt lgkmcnt(0)
	s_cmp_lg_u32 s93, 0
	s_cbranch_scc1 .Lp9dead0
	v_mfma_f32_16x16x32_bf16 v[124:127], v[148:151], v[180:183], v[124:127]
	v_mfma_f32_16x16x32_bf16 v[120:123], v[156:159], v[180:183], v[120:123]
	v_mfma_f32_16x16x32_bf16 v[108:111], v[148:151], v[192:195], v[108:111]
	v_mfma_f32_16x16x32_bf16 v[104:107], v[156:159], v[192:195], v[104:107]
	v_mfma_f32_16x16x32_bf16 v[92:95], v[148:151], v[200:203], v[92:95]
	v_mfma_f32_16x16x32_bf16 v[88:91], v[156:159], v[200:203], v[88:91]
	v_mfma_f32_16x16x32_bf16 v[76:79], v[148:151], v[208:211], v[76:79]
	v_mfma_f32_16x16x32_bf16 v[72:75], v[156:159], v[208:211], v[72:75]
	v_mfma_f32_16x16x32_bf16 v[124:127], v[152:155], v[184:187], v[124:127]
	v_mfma_f32_16x16x32_bf16 v[120:123], v[160:163], v[184:187], v[120:123]
	v_mfma_f32_16x16x32_bf16 v[108:111], v[152:155], v[196:199], v[108:111]
	v_mfma_f32_16x16x32_bf16 v[104:107], v[160:163], v[196:199], v[104:107]
	v_mfma_f32_16x16x32_bf16 v[92:95], v[152:155], v[204:207], v[92:95]
	v_mfma_f32_16x16x32_bf16 v[88:91], v[160:163], v[204:207], v[88:91]
	v_mfma_f32_16x16x32_bf16 v[76:79], v[152:155], v[212:215], v[76:79]
	v_mfma_f32_16x16x32_bf16 v[72:75], v[160:163], v[212:215], v[72:75]
.Lp9dead0:
	s_setprio 0
	s_setprio 1
	s_cmp_lg_u32 s93, 0
	s_cbranch_scc1 .Lp9dead1
	v_mfma_f32_16x16x32_bf16 v[116:119], v[164:167], v[180:183], v[116:119]
	v_mfma_f32_16x16x32_bf16 v[112:115], v[172:175], v[180:183], v[112:115]
	v_mfma_f32_16x16x32_bf16 v[100:103], v[164:167], v[192:195], v[100:103]
	v_mfma_f32_16x16x32_bf16 v[96:99], v[172:175], v[192:195], v[96:99]
	v_mfma_f32_16x16x32_bf16 v[84:87], v[164:167], v[200:203], v[84:87]
	v_mfma_f32_16x16x32_bf16 v[80:83], v[172:175], v[200:203], v[80:83]
	v_mfma_f32_16x16x32_bf16 v[68:71], v[164:167], v[208:211], v[68:71]
	v_mfma_f32_16x16x32_bf16 v[64:67], v[172:175], v[208:211], v[64:67]
	v_mfma_f32_16x16x32_bf16 v[116:119], v[168:171], v[184:187], v[116:119]
	v_mfma_f32_16x16x32_bf16 v[112:115], v[176:179], v[184:187], v[112:115]
	v_mfma_f32_16x16x32_bf16 v[100:103], v[168:171], v[196:199], v[100:103]
	v_mfma_f32_16x16x32_bf16 v[96:99], v[176:179], v[196:199], v[96:99]
	v_mfma_f32_16x16x32_bf16 v[84:87], v[168:171], v[204:207], v[84:87]
	v_mfma_f32_16x16x32_bf16 v[80:83], v[176:179], v[204:207], v[80:83]
	v_mfma_f32_16x16x32_bf16 v[68:71], v[168:171], v[212:215], v[68:71]
	v_mfma_f32_16x16x32_bf16 v[64:67], v[176:179], v[212:215], v[64:67]
.Lp9dead1:
	s_setprio 0
	s_barrier
	s_add_i32 s72, s73, s63
	s_mov_b32 m0, s72
	ds_read_b128 v[180:183], v147 offset:16384
	ds_read_b128 v[184:187], v147 offset:17408
	ds_read_b128 v[192:195], v147 offset:18432
	ds_read_b128 v[196:199], v147 offset:19456
	ds_read_b128 v[200:203], v147 offset:20480
	ds_read_b128 v[204:207], v147 offset:21504
	ds_read_b128 v[208:211], v147 offset:22528
	ds_read_b128 v[212:215], v147 offset:23552
	global_load_lds_dwordx4 v130, s[36:37]
	s_add_i32 m0, s72, 0x2000
	s_add_u32 s72, s36, 0x40000
	s_addc_u32 s73, s37, 0
	s_add_i32 s74, s74, s63
	global_load_lds_dwordx4 v136, s[36:37]
	s_mov_b32 m0, s74
	s_mov_b64 s[98:99], s[42:43]
	global_load_lds_dwordx4 v130, s[72:73]
	s_add_i32 m0, s74, 0x2000
	s_nop 0
	global_load_lds_dwordx4 v136, s[72:73]
	s_mov_b32 m0, s64
	s_nop 0
	global_load_lds_dwordx4 v132, s[42:43]
	s_mov_b32 m0, s65
	s_nop 0
	global_load_lds_dwordx4 v134, s[42:43]
	s_waitcnt vmcnt(8)
	s_waitcnt lgkmcnt(0)
	s_barrier
	s_setprio 1
	s_waitcnt lgkmcnt(0)
	s_cbranch_vccnz .Lp9dead2
	v_mfma_f32_16x16x32_bf16 v[60:63], v[148:151], v[180:183], v[60:63]
	v_mfma_f32_16x16x32_bf16 v[56:59], v[156:159], v[180:183], v[56:59]
	v_mfma_f32_16x16x32_bf16 v[44:47], v[148:151], v[192:195], v[44:47]
	v_mfma_f32_16x16x32_bf16 v[40:43], v[156:159], v[192:195], v[40:43]
	v_mfma_f32_16x16x32_bf16 v[28:31], v[148:151], v[200:203], v[28:31]
	v_mfma_f32_16x16x32_bf16 v[24:27], v[156:159], v[200:203], v[24:27]
	v_mfma_f32_16x16x32_bf16 v[12:15], v[148:151], v[208:211], v[12:15]
	v_mfma_f32_16x16x32_bf16 v[8:11], v[156:159], v[208:211], v[8:11]
	v_mfma_f32_16x16x32_bf16 v[60:63], v[152:155], v[184:187], v[60:63]
	v_mfma_f32_16x16x32_bf16 v[56:59], v[160:163], v[184:187], v[56:59]
	v_mfma_f32_16x16x32_bf16 v[44:47], v[152:155], v[196:199], v[44:47]
	v_mfma_f32_16x16x32_bf16 v[40:43], v[160:163], v[196:199], v[40:43]
	v_mfma_f32_16x16x32_bf16 v[28:31], v[152:155], v[204:207], v[28:31]
	v_mfma_f32_16x16x32_bf16 v[24:27], v[160:163], v[204:207], v[24:27]
	v_mfma_f32_16x16x32_bf16 v[12:15], v[152:155], v[212:215], v[12:15]
	v_mfma_f32_16x16x32_bf16 v[8:11], v[160:163], v[212:215], v[8:11]
.Lp9dead2:
	s_setprio 0
	s_setprio 1
	s_cbranch_vccnz .Lp9dead3
	v_mfma_f32_16x16x32_bf16 v[52:55], v[164:167], v[180:183], v[52:55]
	v_mfma_f32_16x16x32_bf16 v[48:51], v[172:175], v[180:183], v[48:51]
	v_mfma_f32_16x16x32_bf16 v[36:39], v[164:167], v[192:195], v[36:39]
	v_mfma_f32_16x16x32_bf16 v[32:35], v[172:175], v[192:195], v[32:35]
	v_mfma_f32_16x16x32_bf16 v[20:23], v[164:167], v[200:203], v[20:23]
	v_mfma_f32_16x16x32_bf16 v[16:19], v[172:175], v[200:203], v[16:19]
	v_mfma_f32_16x16x32_bf16 v[4:7], v[164:167], v[208:211], v[4:7]
	v_mfma_f32_16x16x32_bf16 v[0:3], v[172:175], v[208:211], v[0:3]
	v_mfma_f32_16x16x32_bf16 v[52:55], v[168:171], v[184:187], v[52:55]
	v_mfma_f32_16x16x32_bf16 v[48:51], v[176:179], v[184:187], v[48:51]
	v_mfma_f32_16x16x32_bf16 v[36:39], v[168:171], v[196:199], v[36:39]
	v_mfma_f32_16x16x32_bf16 v[32:35], v[176:179], v[196:199], v[32:35]
	v_mfma_f32_16x16x32_bf16 v[20:23], v[168:171], v[204:207], v[20:23]
	v_mfma_f32_16x16x32_bf16 v[16:19], v[176:179], v[204:207], v[16:19]
	v_mfma_f32_16x16x32_bf16 v[4:7], v[168:171], v[212:215], v[4:7]
	v_mfma_f32_16x16x32_bf16 v[0:3], v[176:179], v[212:215], v[0:3]
.Lp9dead3:
	s_setprio 0
	s_barrier
	s_add_i32 s72, 0, 0x18000
	s_add_i32 s73, 0, 0x1c000
	v_add_u32_e32 v160, s72, v146
	v_add_u32_e32 v176, s73, v146
	ds_read_b128 v[148:151], v160
	ds_read_b128 v[152:155], v160 offset:1024
	ds_read_b128 v[156:159], v160 offset:2048
	ds_read_b128 v[160:163], v160 offset:3072
	ds_read_b128 v[164:167], v176
	ds_read_b128 v[168:171], v176 offset:1024
	ds_read_b128 v[172:175], v176 offset:2048
	ds_read_b128 v[176:179], v176 offset:3072
	s_add_u32 s42, s42, 0x40000
	s_addc_u32 s43, s43, 0
	s_mov_b32 m0, s66
	ds_read_b128 v[180:183], v147 offset:32768
	ds_read_b128 v[184:187], v147 offset:33792
	ds_read_b128 v[192:195], v147 offset:34816
	ds_read_b128 v[196:199], v147 offset:35840
	ds_read_b128 v[200:203], v147 offset:36864
	ds_read_b128 v[204:207], v147 offset:37888
	ds_read_b128 v[208:211], v147 offset:38912
	ds_read_b128 v[212:215], v147 offset:39936
	global_load_lds_dwordx4 v132, s[42:43]
	s_mov_b32 m0, s67
	s_nop 0
	global_load_lds_dwordx4 v134, s[42:43]
	s_waitcnt vmcnt(8)
	s_waitcnt lgkmcnt(0)
	s_barrier
	s_setprio 1
	s_waitcnt lgkmcnt(0)
	s_cmp_lg_u32 s93, 0
	s_cbranch_scc1 .Lp9dead4
	v_mfma_f32_16x16x32_bf16 v[124:127], v[148:151], v[180:183], v[124:127]
	v_mfma_f32_16x16x32_bf16 v[120:123], v[156:159], v[180:183], v[120:123]
	v_mfma_f32_16x16x32_bf16 v[108:111], v[148:151], v[192:195], v[108:111]
	v_mfma_f32_16x16x32_bf16 v[104:107], v[156:159], v[192:195], v[104:107]
	v_mfma_f32_16x16x32_bf16 v[92:95], v[148:151], v[200:203], v[92:95]
	v_mfma_f32_16x16x32_bf16 v[88:91], v[156:159], v[200:203], v[88:91]
	v_mfma_f32_16x16x32_bf16 v[76:79], v[148:151], v[208:211], v[76:79]
	v_mfma_f32_16x16x32_bf16 v[72:75], v[156:159], v[208:211], v[72:75]
	v_mfma_f32_16x16x32_bf16 v[124:127], v[152:155], v[184:187], v[124:127]
	v_mfma_f32_16x16x32_bf16 v[120:123], v[160:163], v[184:187], v[120:123]
	v_mfma_f32_16x16x32_bf16 v[108:111], v[152:155], v[196:199], v[108:111]
	v_mfma_f32_16x16x32_bf16 v[104:107], v[160:163], v[196:199], v[104:107]
	v_mfma_f32_16x16x32_bf16 v[92:95], v[152:155], v[204:207], v[92:95]
	v_mfma_f32_16x16x32_bf16 v[88:91], v[160:163], v[204:207], v[88:91]
	v_mfma_f32_16x16x32_bf16 v[76:79], v[152:155], v[212:215], v[76:79]
	v_mfma_f32_16x16x32_bf16 v[72:75], v[160:163], v[212:215], v[72:75]

.Lp9dead5:
	s_setprio 0
	s_barrier
	s_add_i32 s42, s72, s63
	s_add_i32 m0, s42, 0xffffff80
	ds_read_b128 v[180:183], v147 offset:49152
	ds_read_b128 v[184:187], v147 offset:50176
	ds_read_b128 v[192:195], v147 offset:51200
	ds_read_b128 v[196:199], v147 offset:52224
	ds_read_b128 v[200:203], v147 offset:53248
	ds_read_b128 v[204:207], v147 offset:54272
	ds_read_b128 v[208:211], v147 offset:55296
	ds_read_b128 v[212:215], v147 offset:56320
	global_load_lds_dwordx4 v130, s[36:37] offset:128
	s_add_i32 m0, s42, 0x1f80
	s_add_i32 s42, s73, s63
	global_load_lds_dwordx4 v136, s[36:37] offset:128
	s_add_u32 s36, s36, 0x40080
	s_addc_u32 s37, s37, 0
	s_mov_b32 m0, s42
	s_nop 0
	global_load_lds_dwordx4 v130, s[36:37]
	s_add_i32 m0, s42, 0x2000
	s_nop 0
	global_load_lds_dwordx4 v136, s[36:37]
	s_add_i32 m0, s68, 0xffffff80
	s_nop 0
	global_load_lds_dwordx4 v132, s[98:99] offset:128
	s_add_i32 m0, s69, 0xffffff80
	s_nop 0
	global_load_lds_dwordx4 v134, s[98:99] offset:128
	s_waitcnt vmcnt(8)
	s_waitcnt lgkmcnt(0)
	s_barrier
	s_setprio 1
	s_waitcnt lgkmcnt(0)
	s_cbranch_vccnz .Lp9dead6
	v_mfma_f32_16x16x32_bf16 v[60:63], v[148:151], v[180:183], v[60:63]
	v_mfma_f32_16x16x32_bf16 v[56:59], v[156:159], v[180:183], v[56:59]
	v_mfma_f32_16x16x32_bf16 v[44:47], v[148:151], v[192:195], v[44:47]
	v_mfma_f32_16x16x32_bf16 v[40:43], v[156:159], v[192:195], v[40:43]
	v_mfma_f32_16x16x32_bf16 v[28:31], v[148:151], v[200:203], v[28:31]
	v_mfma_f32_16x16x32_bf16 v[24:27], v[156:159], v[200:203], v[24:27]
	v_mfma_f32_16x16x32_bf16 v[12:15], v[148:151], v[208:211], v[12:15]
	v_mfma_f32_16x16x32_bf16 v[8:11], v[156:159], v[208:211], v[8:11]
	v_mfma_f32_16x16x32_bf16 v[60:63], v[152:155], v[184:187], v[60:63]
	v_mfma_f32_16x16x32_bf16 v[56:59], v[160:163], v[184:187], v[56:59]
	v_mfma_f32_16x16x32_bf16 v[44:47], v[152:155], v[196:199], v[44:47]
	v_mfma_f32_16x16x32_bf16 v[40:43], v[160:163], v[196:199], v[40:43]
	v_mfma_f32_16x16x32_bf16 v[28:31], v[152:155], v[204:207], v[28:31]
	v_mfma_f32_16x16x32_bf16 v[24:27], v[160:163], v[204:207], v[24:27]
	v_mfma_f32_16x16x32_bf16 v[12:15], v[152:155], v[212:215], v[12:15]
	v_mfma_f32_16x16x32_bf16 v[8:11], v[160:163], v[212:215], v[8:11]

.Lp9dead7:
	s_setprio 0
	s_barrier
	s_add_u32 s28, s28, 0x100
	s_addc_u32 s29, s29, 0
	s_cmp_ge_i32 s71, s62
	s_mov_b32 s36, s71
	s_cbranch_scc0 .LBB0_1033
	s_cmpk_lt_u32 s60, 0x100
	s_cbranch_scc0 .LBB0_1036
